# SEL attention loop: K/V staged as tile pairs in 4 LDS slots, one workgroup barrier per two key tiles
# speedup vs baseline: 1.0393x; 1.0120x over previous
; DI float bflo(unsigned w) { return __uint_as_float(w << 16); }
; DI float bfhi(unsigned w) { return __uint_as_float(w & 0xffff0000u); }
; #define GATES WSP(float, WS_GATES)
; #define MASKS WSP(unsigned, WS_MASK)
; #define lds fresh_lds(lds0)
; template <int DQK, int MODE> ...
;     ...
;     FL_GLOAD(t0);
;     __syncthreads();
;     FL_LSTORE(0);
;     if (t0 + 1 < t1) FL_GLOAD(t0 + 1);
;     __syncthreads();
; __global__ void __launch_bounds__(512) mega_fwd(Params P) {
;     ...
;                 const int qb = 31 - it / 24, r24 = it % 24, bh = r24 % 12, b = bh / 6, h = bh % 6, g = h / 3, q0 = qb * 256;
;                 const size_t rb = (size_t)b * SEQ; const size_t qrow = rb + q0 + 32 * wid + r32;
;                 if (r24 < 12) {
;                     f32x16 tot[2]; tot[0] = (f32x16){}; tot[1] = (f32x16){};
;                     flash_unit<96, MODE_CAUSAL>(lds, wv0, QMLA + (rb + q0) * 576 + h * 96, 576, KVB + rb * 768 + h * 64, 768, PROJ + rb * NPROJ + PC_KR, NPROJ,
;                                                 KVB + rb * 768 + 384 + h * 64, 768, q0, 0, (q0 + 256) / 64, 0.10206207261596577f * LOG2E, (u32x4){}, 1.f, tot, nullptr, WSP(float, WS_ROPE));
;                     store_o(tot, HN + qrow * DM + h * 64, hi);
;                 } else {
;                     const float g1 = GATES[qrow * 32 + h * 3 + 1], g2 = GATES[qrow * 32 + h * 3 + 2];
;                     const u32x4 mw = *(const u32x4*)(MASKS + ((size_t)(b * 2 + g) * SEQ + q0 + 32 * wid + r32) * 4);
;                     f32x16 tot[2];
;                     { const bf16_t* oc = OCMP + qrow * 384 + h * 64;
; #pragma unroll
;                       for (int d0 = 0; d0 < 2; ++d0)
; #pragma unroll
;                           for (int j = 0; j < 4; ++j) { const u32x2 w = *(const u32x2*)(oc + 32 * d0 + 8 * j + 4 * hi); tot[d0][4 * j] = bflo(w.x); tot[d0][4 * j + 1] = bfhi(w.x); tot[d0][4 * j + 2] = bflo(w.y); tot[d0][4 * j + 3] = bfhi(w.y); } }
;                     const bf16_t* Qp = PROJ + (rb + q0) * NPROJ + PC_NQ + 64 * h;
;                     flash_unit<64, MODE_SEL>(lds, wv0, Qp, NPROJ, PROJ + rb * NPROJ + PC_KS + 64 * g, NPROJ, nullptr, 0, PROJ + rb * NPROJ + PC_VS + 64 * g, NPROJ,
;                                              q0, 0, (q0 + 256) / 64, 0.125f * LOG2E, mw, g1, tot, nullptr);
.LBB0_1306:
	s_or_b64 exec, exec, s[0:1]
	v_mov_b32_e32 v0, s38
	s_waitcnt lgkmcnt(0)
	s_barrier
	ds_read_b32 v0, v0
	s_movk_i32 s0, 0x3ff
	s_waitcnt lgkmcnt(0)
	v_cmp_lt_i32_e32 vcc, s0, v0
	v_readfirstlane_b32 s34, v0
	s_mov_b64 s[0:1], -1
	s_cbranch_vccnz .LBB0_1303
	s_cmpk_lt_i32 s34, 0x300
	s_cbranch_scc0 .LBB0_1372
	s_mul_hi_i32 s0, s34, 0xd5555555
	s_lshr_b32 s1, s0, 31
	s_lshr_b32 s0, s0, 2
	s_add_i32 s4, s0, s1
	s_mul_hi_i32 s0, s34, 0x2aaaaaab
	s_lshr_b32 s1, s0, 31
	s_lshr_b32 s0, s0, 2
	s_add_i32 s0, s0, s1
	s_mul_i32 s0, s0, 24
	s_sub_i32 s6, s34, s0
	s_mul_i32 s0, s6, 43
	s_sext_i32_i16 s1, s0
	s_lshr_b32 s1, s1, 9
	s_bfe_u32 s0, s0, 0x1000f
	s_add_i32 s0, s1, s0
	s_mul_i32 s0, s0, 12
	s_sub_i32 s1, s6, s0
	s_bfe_i32 s0, s1, 0x80000
	s_mul_i32 s0, s0, 43
	s_bfe_u32 s5, s0, 0x1000f
	s_bfe_u32 s0, s0, 0x80008
	s_add_i32 s0, s0, s5
	s_mul_i32 s5, s0, 6
	s_sub_i32 s1, s1, s5
	s_lshl_b32 s35, s4, 8
	s_bfe_i64 s[8:9], s[0:1], 0x80000
	s_add_i32 s36, s35, 0x1f00
	s_lshl_b64 s[4:5], s[8:9], 13
	s_add_u32 s26, s4, s36
	s_addc_u32 s27, s5, 0
	s_sext_i32_i8 s37, s1
	v_lshl_add_u64 v[180:181], s[26:27], 0, v[174:175]
	s_mov_b64 s[4:5], -1
	s_cmp_gt_i32 s6, 11
	s_mul_hi_i32 s45, s8, 0x2800000
	s_mul_i32 s46, s8, 0x2800000
	s_cbranch_scc0 .LBB0_1346
	s_bfe_i32 s1, s1, 0x80000
	s_mulk_i32 s1, 0x56
	s_bfe_u32 s4, s1, 0x1000f
	s_bfe_u32 s1, s1, 0x80008
	s_add_i32 s1, s1, s4
	s_sext_i32_i8 s6, s1
	s_sext_i32_i8 s0, s0
	s_lshl_b32 s0, s0, 14
	s_lshl_b32 s1, s6, 13
	s_add_i32 s1, s1, s0
	s_add_u32 s0, s1, s36
	s_addc_u32 s1, 0, 0
	v_mov_b64_e32 v[6:7], s[18:19]
	v_lshl_add_u64 v[4:5], s[0:1], 0, v[174:175]
	v_mad_u64_u32 v[6:7], s[0:1], v180, s72, v[6:7]
	v_mov_b32_e32 v0, v7
	v_lshlrev_b64 v[2:3], 7, v[180:181]
	v_mad_u64_u32 v[8:9], s[0:1], v181, s72, v[0:1]
	s_mul_i32 s80, s37, 3
	v_lshl_add_u64 v[2:3], s[14:15], 0, v[2:3]
	s_mul_i32 s0, s27, 0x1400
	s_mul_hi_u32 s1, s26, 0x1400
	v_lshl_add_u64 v[2:3], s[80:81], 2, v[2:3]
	s_lshl_b32 s9, s37, 6
	s_lshl_b32 s80, s37, 7
	s_add_i32 s1, s1, s0
	s_mul_i32 s0, s26, 0x1400
	s_add_u32 s0, s39, s0
	v_mov_b32_e32 v7, v8
	s_addc_u32 s1, s40, s1
	v_lshl_add_u64 v[6:7], v[6:7], 0, s[80:81]
	v_mov_b32_e32 v179, v1
	s_add_u32 s30, s0, s80
	v_lshl_add_u64 v[4:5], v[4:5], 4, s[16:17]
	v_lshl_add_u64 v[6:7], v[6:7], 0, v[178:179]
	s_addc_u32 s31, s1, 0
	s_mov_b32 s1, s81
	v_mov_b32_e32 v0, v1
	flat_load_dwordx2 v[182:183], v[2:3] offset:4
	s_nop 0
	flat_load_dwordx4 v[2:5], v[4:5]
	s_nop 0
	flat_load_dwordx2 v[198:199], v[6:7]
	flat_load_dwordx2 v[196:197], v[6:7] offset:16
	flat_load_dwordx2 v[194:195], v[6:7] offset:32
	flat_load_dwordx2 v[192:193], v[6:7] offset:48
	flat_load_dwordx2 v[190:191], v[6:7] offset:64
	flat_load_dwordx2 v[188:189], v[6:7] offset:80
	flat_load_dwordx2 v[186:187], v[6:7] offset:96
	flat_load_dwordx2 v[184:185], v[6:7] offset:112
	v_readlane_b32 s7, v254, 6
	v_mbcnt_lo_u32_b32 v0, -1, v0
	v_mbcnt_hi_u32_b32 v26, -1, v0
	v_and_b32_e32 v27, 31, v26
	v_bfe_u32 v28, v26, 5, 1
	v_or_b32_e32 v0, s7, v27
	v_mov_b64_e32 v[6:7], s[30:31]
	v_mad_i64_i32 v[6:7], s[4:5], v0, s69, v[6:7]
	v_lshlrev_b32_e32 v0, 4, v28
	v_lshl_add_u64 v[6:7], v[6:7], 0, v[0:1]
	s_waitcnt vmcnt(0)
	flat_load_dwordx4 v[84:87], v[6:7] offset:832
	flat_load_dwordx4 v[80:83], v[6:7] offset:864
	flat_load_dwordx4 v[10:13], v[6:7] offset:896
	s_nop 0
	flat_load_dwordx4 v[6:9], v[6:7] offset:928
	s_add_u32 s0, s39, s46
	v_or_b32_e32 v14, s79, v26
	s_addc_u32 s4, s40, s45
	s_lshl_b32 s5, s6, 7
	v_and_b32_e32 v15, 7, v26
	v_ashrrev_i32_e32 v24, 3, v14
	s_add_u32 s28, s0, s5
	v_lshlrev_b32_e32 v29, 4, v15
	v_mul_lo_u32 v14, v24, s69
	v_mov_b32_e32 v23, v1
	s_addc_u32 s29, s4, 0
	v_or_b32_e32 v22, v29, v14
	v_lshl_add_u64 v[18:19], s[28:29], 0, v[22:23]
	s_movk_i32 s4, 0x90
	v_mul_lo_u32 v23, v24, s4
	v_mov_b32_e32 v25, v1
	v_add3_u32 v129, s1, v23, v29
	v_add_u32_e32 v24, 0x50000, v22
	v_lshl_add_u64 v[24:25], s[28:29], 0, v[24:25]
	v_add_u32_e32 v226, 0xa0000, v22
	v_mov_b32_e32 v227, v1
	v_lshl_add_u64 v[226:227], s[28:29], 0, v[226:227]
	v_add_u32_e32 v232, 0xf0000, v22
	v_mov_b32_e32 v233, v1
	v_lshl_add_u64 v[232:233], s[28:29], 0, v[232:233]
	v_mad_u32_u24 v131, v27, s4, v0
	v_lshlrev_b32_e32 v128, 2, v28
	v_lshrrev_b32_e32 v0, 2, v26
	s_add_i32 s0, s35, 0x2000
	s_add_i32 s48, s36, s7
	v_and_or_b32 v0, v0, 3, v128
	v_mov_b32_e32 v30, v1
	v_mov_b32_e32 v31, v1
	s_lshr_b32 s47, s0, 6
	v_mov_b32_e32 v23, v1
	v_mov_b32_e32 v28, v1
	v_mov_b32_e32 v29, v1
	s_mov_b32 s53, s81
	s_mov_b32 s50, 0
	s_or_b32 s49, s48, 31
	s_add_i32 s0, s47, -1
	v_mov_b32_e32 v179, 0
	s_mov_b32 s51, 63
	s_waitcnt vmcnt(0) lgkmcnt(0)
	global_load_dwordx4 v[14:17], v[18:19], off offset:2112
	s_nop 0
	global_load_dwordx4 v[18:21], v[18:19], off offset:2368
	global_load_dwordx4 v[88:91], v[24:25], off offset:2368
	global_load_dwordx4 v[92:95], v[24:25], off offset:2112
	s_waitcnt lgkmcnt(0)
	s_barrier
	s_waitcnt vmcnt(0)
	ds_write_b128 v129, v[14:17]
	ds_write_b128 v129, v[18:21] offset:36864
	v_add_u32_e32 v229, 0x2400, v129
	ds_write_b128 v229, v[92:95]
	ds_write_b128 v229, v[88:91] offset:36864
	global_load_dwordx4 v[88:91], v[226:227], off offset:2368
	global_load_dwordx4 v[92:95], v[226:227], off offset:2112
	global_load_dwordx4 v[222:225], v[232:233], off offset:2368
	global_load_dwordx4 v[218:221], v[232:233], off offset:2112
	v_lshlrev_b32_e32 v14, 1, v26
	v_and_b32_e32 v14, 32, v14
	v_lshlrev_b32_e32 v16, 3, v26
	v_and_or_b32 v14, v16, 24, v14
	v_or_b32_e32 v15, s48, v27
	v_mad_u32_u24 v130, v0, s4, v14
	v_add_u32_e32 v0, 0xf0000, v22
	v_mov_b32_e32 v16, v1
	v_mov_b32_e32 v17, v1
	v_mov_b32_e32 v18, v1
	v_mov_b32_e32 v19, v1
	v_mov_b32_e32 v20, v1
	v_mov_b32_e32 v21, v1
	v_mov_b32_e32 v22, v1
	v_mov_b32_e32 v24, v1
	v_mov_b32_e32 v25, v1
	v_mov_b32_e32 v26, v1
	v_mov_b32_e32 v27, v1
	v_mov_b64_e32 v[46:47], v[30:31]
	v_mov_b32_e32 v14, 0xf149f2ca
	v_mov_b64_e32 v[44:45], v[28:29]
	v_mov_b64_e32 v[42:43], v[26:27]
	v_mov_b64_e32 v[40:41], v[24:25]
	v_mov_b64_e32 v[38:39], v[22:23]
	v_mov_b64_e32 v[36:37], v[20:21]
	v_mov_b64_e32 v[34:35], v[18:19]
	v_mov_b64_e32 v[32:33], v[16:17]
	s_waitcnt lgkmcnt(0)
	s_barrier
	s_branch .LBB0_1311

; #define lds fresh_lds(lds0)
; template <int DQK, int MODE> ...
;     ...
;         const int cur = (t - t0) & 1;
;         const LAS unsigned char* Ks = lds + AT_K + cur * KBUF; const LAS unsigned char* Vs = lds + AT_V + cur * VBUF;
;         bool active = true;
;         if (MODE == MODE_CAUSAL || MODE == MODE_SEL || MODE == MODE_WIN) active = (64 * t <= qmax);
;         if (MODE == MODE_WIN) active = active && (64 * t + 63 + 512 > qmin);
;         if (MODE == MODE_CMP) active = (16 * (64 * t) + 31 <= qmax);
;         if (active) {
;             f32x16 s[2];
;             bf16x8 ka[2][NKS]; s16x4 vlo[2][2][2], vhi[2][2][2];
;             {
;                 const unsigned kaddr = (unsigned)(unsigned long)(lds + AT_K + cur * KBUF) + (unsigned)(r32 * KP2 + hi * 16);
;                 const unsigned vaddr = (unsigned)(unsigned long)(lds + AT_V + cur * VBUF) + (unsigned)((4 * hi + ((lane & 15) >> 2)) * VP2 + 32 * ((lane >> 4) & 1) + 8 * (lane & 3));
; #pragma unroll
;                 for (int kb = 0; kb < 2; ++kb)
; #pragma unroll
;                     for (int ks = 0; ks < NKS; ++ks) asm volatile("ds_read_b128 %0, %1 offset:%2" : "=v"(ka[kb][ks]) : "v"(kaddr), "n"(kb * 32 * KP2 + ks * 32) : "memory");
; #pragma unroll
;                 for (int s2 = 0; s2 < 2; ++s2)
; #pragma unroll
;                     for (int d0 = 0; d0 < 2; ++d0) {
;                         asm volatile("ds_read_b64_tr_b16 %0, %1 offset:%2" : "=v"(vlo[0][s2][d0]) : "v"(vaddr), "n"(16 * s2 * VP2 + 64 * d0) : "memory");
;                         asm volatile("ds_read_b64_tr_b16 %0, %1 offset:%2" : "=v"(vhi[0][s2][d0]) : "v"(vaddr), "n"(16 * s2 * VP2 + 64 * d0 + 8 * VP2) : "memory");
;                     }
;                 asm volatile("s_waitcnt lgkmcnt(8)" ::: "memory");
; #pragma unroll
;                 for (int kb = 0; kb < 2; ++kb)
; #pragma unroll
;                     for (int ks = 0; ks < NKS; ++ks) asm volatile("" : "+v"(ka[kb][ks]));
;                 s[0] = (f32x16){}; s[1] = (f32x16){};
;                 __builtin_amdgcn_s_setprio(1);
; #pragma unroll
;                 for (int ks = 0; ks < NKS; ++ks) { s[0] = MFMA32(ka[0][ks], qf[ks], s[0]); s[1] = MFMA32(ka[1][ks], qf[ks], s[1]); }
;                 __builtin_amdgcn_s_setprio(0);
; #pragma unroll
;                 for (int s2 = 0; s2 < 2; ++s2)
; #pragma unroll
;                     for (int d0 = 0; d0 < 2; ++d0) {
.LBB0_1311:
	s_and_b32 s52, s50, 3
	s_sub_i32 s4, s51, 63
	s_cmp_gt_i32 s4, s49
	s_cbranch_scc1 .LBB0_1319
	s_mul_i32 s4, s52, 0x2400
	s_add_i32 s4, s1, s4
	v_add_u32_e32 v52, s4, v131
	ds_read_b128 v[64:67], v52 offset:0
	ds_read_b128 v[104:107], v52 offset:32
	ds_read_b128 v[108:111], v52 offset:64
	ds_read_b128 v[132:135], v52 offset:0x60
	ds_read_b128 v[48:51], v52 offset:0x1200
	ds_read_b128 v[68:71], v52 offset:0x1220
	ds_read_b128 v[72:75], v52 offset:0x1240
	s_add_i32 s4, s4, 0x9000
	ds_read_b128 v[76:79], v52 offset:0x1260
	v_add_u32_e32 v136, s4, v130
	ds_read_b64_tr_b16 v[116:117], v136 offset:0
	ds_read_b64_tr_b16 v[118:119], v136 offset:0x480
	ds_read_b64_tr_b16 v[112:113], v136 offset:64
	ds_read_b64_tr_b16 v[114:115], v136 offset:0x4c0
	ds_read_b64_tr_b16 v[100:101], v136 offset:0x900
	ds_read_b64_tr_b16 v[102:103], v136 offset:0xd80
	ds_read_b64_tr_b16 v[96:97], v136 offset:0x940
	ds_read_b64_tr_b16 v[98:99], v136 offset:0xdc0
	s_waitcnt lgkmcnt(8)
	s_setprio 1
	v_mfma_f32_32x32x16_bf16 v[48:63], v[48:51], v[84:87], 0
	v_mfma_f32_32x32x16_bf16 v[48:63], v[68:71], v[80:83], v[48:63]
	v_mfma_f32_32x32x16_bf16 v[48:63], v[72:75], v[10:13], v[48:63]
	v_mfma_f32_32x32x16_bf16 v[48:63], v[76:79], v[6:9], v[48:63]
	s_setprio 0
	v_mfma_f32_32x32x16_bf16 v[64:79], v[64:67], v[84:87], 0
	ds_read_b64_tr_b16 v[124:125], v136 offset:0x1200
	ds_read_b64_tr_b16 v[126:127], v136 offset:0x1680
	ds_read_b64_tr_b16 v[120:121], v136 offset:0x1240
	ds_read_b64_tr_b16 v[122:123], v136 offset:0x16c0
	s_cmp_le_i32 s51, s48
	v_mfma_f32_32x32x16_bf16 v[64:79], v[104:107], v[80:83], v[64:79]
	v_mfma_f32_32x32x16_bf16 v[64:79], v[108:111], v[10:13], v[64:79]
	ds_read_b64_tr_b16 v[108:109], v136 offset:0x1b00
	ds_read_b64_tr_b16 v[110:111], v136 offset:0x1f80
	ds_read_b64_tr_b16 v[104:105], v136 offset:0x1b40
	ds_read_b64_tr_b16 v[106:107], v136 offset:0x1fc0
	v_mfma_f32_32x32x16_bf16 v[64:79], v[132:135], v[6:9], v[64:79]
	s_cbranch_scc1 .LBB0_1314
	v_add_u32_e32 v132, s51, v128
	v_subrev_u32_e32 v133, 63, v132
	v_cmp_le_i32_e32 vcc, v133, v15
	s_nop 7
	v_cndmask_b32_e32 v64, v204, v64, vcc
	v_cmp_lt_i32_e32 vcc, v133, v15
	v_subrev_u32_e32 v133, 61, v132
	s_nop 0
	v_cndmask_b32_e32 v65, v204, v65, vcc
	v_cmp_le_i32_e32 vcc, v133, v15
	v_subrev_u32_e32 v133, 60, v132
	s_nop 0
	v_cndmask_b32_e32 v66, v204, v66, vcc
	v_cmp_le_i32_e32 vcc, v133, v15
	v_subrev_u32_e32 v133, 55, v132
	s_nop 0
	v_cndmask_b32_e32 v67, v204, v67, vcc
	v_cmp_le_i32_e32 vcc, v133, v15
	v_subrev_u32_e32 v133, 54, v132
	s_nop 0
	v_cndmask_b32_e32 v68, v204, v68, vcc
	v_cmp_le_i32_e32 vcc, v133, v15
	v_subrev_u32_e32 v133, 53, v132
	s_nop 0
	v_cndmask_b32_e32 v69, v204, v69, vcc
	v_cmp_le_i32_e32 vcc, v133, v15
	v_subrev_u32_e32 v133, 52, v132
	s_nop 0
	v_cndmask_b32_e32 v70, v204, v70, vcc
	v_cmp_le_i32_e32 vcc, v133, v15
	v_subrev_u32_e32 v133, 47, v132
	s_nop 0
	v_cndmask_b32_e32 v71, v204, v71, vcc
	v_cmp_le_i32_e32 vcc, v133, v15
	v_subrev_u32_e32 v133, 46, v132
	s_nop 0
	v_cndmask_b32_e32 v72, v204, v72, vcc
	v_cmp_le_i32_e32 vcc, v133, v15
	v_subrev_u32_e32 v133, 45, v132
	s_nop 0
	v_cndmask_b32_e32 v73, v204, v73, vcc
	v_cmp_le_i32_e32 vcc, v133, v15
	v_subrev_u32_e32 v133, 44, v132
	s_nop 0
	v_cndmask_b32_e32 v74, v204, v74, vcc
	v_cmp_le_i32_e32 vcc, v133, v15
	v_subrev_u32_e32 v133, 39, v132
	s_nop 0
	v_cndmask_b32_e32 v75, v204, v75, vcc
	v_cmp_le_i32_e32 vcc, v133, v15
	v_subrev_u32_e32 v133, 38, v132
	s_nop 0
	v_cndmask_b32_e32 v76, v204, v76, vcc
	v_cmp_le_i32_e32 vcc, v133, v15
	v_subrev_u32_e32 v133, 37, v132
	s_nop 0
	v_cndmask_b32_e32 v77, v204, v77, vcc
	v_cmp_le_i32_e32 vcc, v133, v15
	v_subrev_u32_e32 v133, 36, v132
	s_nop 0
	v_cndmask_b32_e32 v78, v204, v78, vcc
	v_cmp_le_i32_e32 vcc, v133, v15
	v_subrev_u32_e32 v133, 31, v132
	s_nop 0
	v_cndmask_b32_e32 v79, v204, v79, vcc
	v_cmp_le_i32_e32 vcc, v133, v15
	v_subrev_u32_e32 v133, 30, v132
	s_nop 0
	v_cndmask_b32_e32 v48, v204, v48, vcc
	v_cmp_le_i32_e32 vcc, v133, v15
	v_subrev_u32_e32 v133, 29, v132
	s_nop 0
	v_cndmask_b32_e32 v49, v204, v49, vcc
	v_cmp_le_i32_e32 vcc, v133, v15
	v_subrev_u32_e32 v133, 28, v132
	s_nop 0
	v_cndmask_b32_e32 v50, v204, v50, vcc
	v_cmp_le_i32_e32 vcc, v133, v15
	v_subrev_u32_e32 v133, 23, v132
	s_nop 0
	v_cndmask_b32_e32 v51, v204, v51, vcc
	v_cmp_le_i32_e32 vcc, v133, v15
	v_subrev_u32_e32 v133, 22, v132
	s_nop 0
	v_cndmask_b32_e32 v52, v204, v52, vcc
	v_cmp_le_i32_e32 vcc, v133, v15
	v_subrev_u32_e32 v133, 21, v132
	s_nop 0
	v_cndmask_b32_e32 v53, v204, v53, vcc
	v_cmp_le_i32_e32 vcc, v133, v15
	v_subrev_u32_e32 v133, 20, v132
	s_nop 0
	v_cndmask_b32_e32 v54, v204, v54, vcc
	v_cmp_le_i32_e32 vcc, v133, v15
	v_add_u32_e32 v133, -15, v132
	s_nop 0
	v_cndmask_b32_e32 v55, v204, v55, vcc
	v_cmp_le_i32_e32 vcc, v133, v15
	v_add_u32_e32 v133, -14, v132
	s_nop 0
	v_cndmask_b32_e32 v56, v204, v56, vcc
	v_cmp_le_i32_e32 vcc, v133, v15
	v_add_u32_e32 v133, -13, v132
	s_nop 0
	v_cndmask_b32_e32 v57, v204, v57, vcc
	v_cmp_le_i32_e32 vcc, v133, v15
	v_add_u32_e32 v133, -12, v132
	s_nop 0
	v_cndmask_b32_e32 v58, v204, v58, vcc
	v_cmp_le_i32_e32 vcc, v133, v15
	v_add_u32_e32 v133, -7, v132
	s_nop 0
	v_cndmask_b32_e32 v59, v204, v59, vcc
	v_cmp_le_i32_e32 vcc, v133, v15
	v_add_u32_e32 v133, -6, v132
	s_nop 0
	v_cndmask_b32_e32 v60, v204, v60, vcc
	v_cmp_le_i32_e32 vcc, v133, v15
	v_add_u32_e32 v133, -5, v132
	v_add_u32_e32 v132, -4, v132
	v_cndmask_b32_e32 v61, v204, v61, vcc
	v_cmp_le_i32_e32 vcc, v133, v15
	s_nop 1
	v_cndmask_b32_e32 v62, v204, v62, vcc
	v_cmp_le_i32_e32 vcc, v132, v15
	s_nop 1
	v_cndmask_b32_e32 v63, v204, v63, vcc

; #define lds fresh_lds(lds0)
; template <int DQK, int MODE> ...
;     ...
;             {
;                 const unsigned kaddr = (unsigned)(unsigned long)(lds + AT_K + cur * KBUF) + (unsigned)(r32 * KP2 + hi * 16);
;                 const unsigned vaddr = (unsigned)(unsigned long)(lds + AT_V + cur * VBUF) + (unsigned)((4 * hi + ((lane & 15) >> 2)) * VP2 + 32 * ((lane >> 4) & 1) + 8 * (lane & 3));
; #pragma unroll
;                 for (int kb = 0; kb < 2; ++kb)
; #pragma unroll
;                     for (int ks = 0; ks < NKS; ++ks) asm volatile("ds_read_b128 %0, %1 offset:%2" : "=v"(ka[kb][ks]) : "v"(kaddr), "n"(kb * 32 * KP2 + ks * 32) : "memory");
; #pragma unroll
;                 for (int s2 = 0; s2 < 2; ++s2)
; #pragma unroll
;                     for (int d0 = 0; d0 < 2; ++d0) {
;                         asm volatile("ds_read_b64_tr_b16 %0, %1 offset:%2" : "=v"(vlo[0][s2][d0]) : "v"(vaddr), "n"(16 * s2 * VP2 + 64 * d0) : "memory");
;                         asm volatile("ds_read_b64_tr_b16 %0, %1 offset:%2" : "=v"(vhi[0][s2][d0]) : "v"(vaddr), "n"(16 * s2 * VP2 + 64 * d0 + 8 * VP2) : "memory");
;                     }
;                 asm volatile("s_waitcnt lgkmcnt(8)" ::: "memory");
; #pragma unroll
;                 for (int kb = 0; kb < 2; ++kb)
; #pragma unroll
;                     for (int ks = 0; ks < NKS; ++ks) asm volatile("" : "+v"(ka[kb][ks]));
;                 s[0] = (f32x16){}; s[1] = (f32x16){};
;                 __builtin_amdgcn_s_setprio(1);
; #pragma unroll
;                 for (int ks = 0; ks < NKS; ++ks) { s[0] = MFMA32(ka[0][ks], qf[ks], s[0]); s[1] = MFMA32(ka[1][ks], qf[ks], s[1]); }
;                 __builtin_amdgcn_s_setprio(0);
; #pragma unroll
;                 for (int s2 = 0; s2 < 2; ++s2)
; #pragma unroll
;                     for (int d0 = 0; d0 < 2; ++d0) {
;                         asm volatile("ds_read_b64_tr_b16 %0, %1 offset:%2" : "=v"(vlo[1][s2][d0]) : "v"(vaddr), "n"((32 + 16 * s2) * VP2 + 64 * d0) : "memory");
;                         asm volatile("ds_read_b64_tr_b16 %0, %1 offset:%2" : "=v"(vhi[1][s2][d0]) : "v"(vaddr), "n"((32 + 16 * s2) * VP2 + 64 * d0 + 8 * VP2) : "memory");
;                     }
;             }
;             bool need_mask;
;             if (MODE == MODE_CMP) need_mask = true;
;             else if (MODE == MODE_WIN) need_mask = (64 * t + 63 > qmin) || (64 * t + 512 <= qmax);
.LBB0_1319:
	s_bitcmp1_b32 s50, 0
	s_cbranch_scc0 .Lsel_even
	s_add_i32 s4, s50, 1
	s_and_b32 s4, s4, 3
	s_mulk_i32 s4, 0x2400
	v_add_u32_e32 v229, s4, v129
	s_add_i32 s4, s50, 2
	s_and_b32 s4, s4, 3
	s_mulk_i32 s4, 0x2400
	v_add_u32_e32 v228, s4, v129
	s_waitcnt vmcnt(0)
	ds_write_b128 v229, v[92:95]
	ds_write_b128 v229, v[88:91] offset:36864
	ds_write_b128 v228, v[218:221]
	ds_write_b128 v228, v[222:225] offset:36864
	s_add_i32 s4, s50, 3
	s_cmp_ge_u32 s4, s47
	s_cbranch_scc1 .LBB0_1310
	v_lshl_add_u64 v[230:231], s[28:29], 0, v[0:1]
	global_load_dwordx4 v[92:95], v[230:231], off offset:2112
	global_load_dwordx4 v[88:91], v[230:231], off offset:2368
	v_add_u32_e32 v228, 0x50000, v0
	v_mov_b32_e32 v229, v1
	v_lshl_add_u64 v[228:229], s[28:29], 0, v[228:229]
	global_load_dwordx4 v[218:221], v[228:229], off offset:2112
	global_load_dwordx4 v[222:225], v[228:229], off offset:2368
	s_branch .LBB0_1310
.Lsel_even:
	s_add_i32 s50, s50, 1
	s_add_i32 s51, s51, 64
	s_cmp_eq_u32 s0, s50
	v_add_u32_e32 v0, 0x50000, v0
	s_cbranch_scc1 .LBB0_1321
	s_branch .LBB0_1311
.LBB0_1321:
	s_lshl_b32 s4, s0, 6
	s_cmp_gt_i32 s4, s49
	s_cbranch_scc1 .LBB0_1329
	s_and_b32 s5, s0, 3
	s_mulk_i32 s5, 0x2400
	s_add_i32 s1, s1, s5
	v_add_u32_e32 v0, s1, v131
	ds_read_b128 v[64:67], v0 offset:0
	ds_read_b128 v[104:107], v0 offset:32
	ds_read_b128 v[108:111], v0 offset:64
	ds_read_b128 v[112:115], v0 offset:0x60
	ds_read_b128 v[48:51], v0 offset:0x1200
	ds_read_b128 v[68:71], v0 offset:0x1220
	ds_read_b128 v[72:75], v0 offset:0x1240
	s_add_i32 s1, s1, 0x9000
	ds_read_b128 v[76:79], v0 offset:0x1260
	v_add_u32_e32 v0, s1, v130
	ds_read_b64_tr_b16 v[100:101], v0 offset:0
	ds_read_b64_tr_b16 v[102:103], v0 offset:0x480
	ds_read_b64_tr_b16 v[96:97], v0 offset:64
	ds_read_b64_tr_b16 v[98:99], v0 offset:0x4c0
	s_waitcnt vmcnt(0)
	ds_read_b64_tr_b16 v[92:93], v0 offset:0x900
	ds_read_b64_tr_b16 v[94:95], v0 offset:0xd80
	ds_read_b64_tr_b16 v[88:89], v0 offset:0x940
	ds_read_b64_tr_b16 v[90:91], v0 offset:0xdc0
	s_waitcnt lgkmcnt(8)
	s_setprio 1
	v_mfma_f32_32x32x16_bf16 v[48:63], v[48:51], v[84:87], 0
	v_mfma_f32_32x32x16_bf16 v[48:63], v[68:71], v[80:83], v[48:63]
	v_mfma_f32_32x32x16_bf16 v[48:63], v[72:75], v[10:13], v[48:63]
	v_mfma_f32_32x32x16_bf16 v[48:63], v[76:79], v[6:9], v[48:63]
	s_setprio 0
	v_mfma_f32_32x32x16_bf16 v[64:79], v[64:67], v[84:87], 0
	s_or_b32 s1, s4, 63
	s_cmp_le_i32 s1, s48
	v_mfma_f32_32x32x16_bf16 v[64:79], v[104:107], v[80:83], v[64:79]
	ds_read_b64_tr_b16 v[104:105], v0 offset:0x1200
	ds_read_b64_tr_b16 v[106:107], v0 offset:0x1680
	ds_read_b64_tr_b16 v[84:85], v0 offset:0x1240
	ds_read_b64_tr_b16 v[86:87], v0 offset:0x16c0
	ds_read_b64_tr_b16 v[80:81], v0 offset:0x1b00
	ds_read_b64_tr_b16 v[82:83], v0 offset:0x1f80
	v_mfma_f32_32x32x16_bf16 v[64:79], v[108:111], v[10:13], v[64:79]
	ds_read_b64_tr_b16 v[10:11], v0 offset:0x1b40
	ds_read_b64_tr_b16 v[12:13], v0 offset:0x1fc0
	v_mfma_f32_32x32x16_bf16 v[64:79], v[112:115], v[6:9], v[64:79]
	s_cbranch_scc1 .LBB0_1324
	v_or_b32_e32 v0, s4, v128
	v_cmp_le_i32_e32 vcc, v0, v15
	v_or_b32_e32 v6, 2, v0
	s_nop 7
	v_cndmask_b32_e32 v64, v204, v64, vcc
	v_cmp_lt_i32_e32 vcc, v0, v15
	s_nop 1
	v_cndmask_b32_e32 v65, v204, v65, vcc
	v_cmp_le_i32_e32 vcc, v6, v15
	v_or_b32_e32 v6, 3, v0
	s_nop 0
	v_cndmask_b32_e32 v66, v204, v66, vcc
	v_cmp_le_i32_e32 vcc, v6, v15
	v_or_b32_e32 v6, 8, v0
	s_nop 0
	v_cndmask_b32_e32 v67, v204, v67, vcc
	v_cmp_le_i32_e32 vcc, v6, v15
	v_or_b32_e32 v6, 9, v0
	s_nop 0
	v_cndmask_b32_e32 v68, v204, v68, vcc
	v_cmp_le_i32_e32 vcc, v6, v15
	v_or_b32_e32 v6, 10, v0
	s_nop 0
	v_cndmask_b32_e32 v69, v204, v69, vcc
	v_cmp_le_i32_e32 vcc, v6, v15
	v_or_b32_e32 v6, 11, v0
	s_nop 0
	v_cndmask_b32_e32 v70, v204, v70, vcc
	v_cmp_le_i32_e32 vcc, v6, v15
	v_or_b32_e32 v6, 16, v0
	s_nop 0
	v_cndmask_b32_e32 v71, v204, v71, vcc
	v_cmp_le_i32_e32 vcc, v6, v15
	v_or_b32_e32 v6, 17, v0
	s_nop 0
	v_cndmask_b32_e32 v72, v204, v72, vcc
	v_cmp_le_i32_e32 vcc, v6, v15
	v_or_b32_e32 v6, 18, v0
	s_nop 0
	v_cndmask_b32_e32 v73, v204, v73, vcc
	v_cmp_le_i32_e32 vcc, v6, v15
	v_or_b32_e32 v6, 19, v0
	s_nop 0
	v_cndmask_b32_e32 v74, v204, v74, vcc
	v_cmp_le_i32_e32 vcc, v6, v15
	v_or_b32_e32 v6, 24, v0
	s_nop 0
	v_cndmask_b32_e32 v75, v204, v75, vcc
	v_cmp_le_i32_e32 vcc, v6, v15
	v_or_b32_e32 v6, 25, v0
	s_nop 0
	v_cndmask_b32_e32 v76, v204, v76, vcc
	v_cmp_le_i32_e32 vcc, v6, v15
	v_or_b32_e32 v6, 26, v0
	s_nop 0
	v_cndmask_b32_e32 v77, v204, v77, vcc
	v_cmp_le_i32_e32 vcc, v6, v15
	v_or_b32_e32 v6, 27, v0
	s_nop 0
	v_cndmask_b32_e32 v78, v204, v78, vcc
	v_cmp_le_i32_e32 vcc, v6, v15
	v_or_b32_e32 v6, 32, v0
	s_nop 0
	v_cndmask_b32_e32 v79, v204, v79, vcc
	v_cmp_le_i32_e32 vcc, v6, v15
	v_or_b32_e32 v6, 33, v0
	s_nop 0
	v_cndmask_b32_e32 v48, v204, v48, vcc
	v_cmp_le_i32_e32 vcc, v6, v15
	v_or_b32_e32 v6, 34, v0
	s_nop 0
	v_cndmask_b32_e32 v49, v204, v49, vcc
	v_cmp_le_i32_e32 vcc, v6, v15
	v_or_b32_e32 v6, 35, v0
	s_nop 0
	v_cndmask_b32_e32 v50, v204, v50, vcc
	v_cmp_le_i32_e32 vcc, v6, v15
	v_or_b32_e32 v6, 40, v0
	s_nop 0
	v_cndmask_b32_e32 v51, v204, v51, vcc
	v_cmp_le_i32_e32 vcc, v6, v15
	v_or_b32_e32 v6, 41, v0
	s_nop 0
	v_cndmask_b32_e32 v52, v204, v52, vcc
	v_cmp_le_i32_e32 vcc, v6, v15
	v_or_b32_e32 v6, 42, v0
	s_nop 0
	v_cndmask_b32_e32 v53, v204, v53, vcc
	v_cmp_le_i32_e32 vcc, v6, v15
	v_or_b32_e32 v6, 43, v0
	s_nop 0
	v_cndmask_b32_e32 v54, v204, v54, vcc
	v_cmp_le_i32_e32 vcc, v6, v15
	v_or_b32_e32 v6, 48, v0
	s_nop 0
	v_cndmask_b32_e32 v55, v204, v55, vcc
	v_cmp_le_i32_e32 vcc, v6, v15
	v_or_b32_e32 v6, 49, v0
	s_nop 0
	v_cndmask_b32_e32 v56, v204, v56, vcc
	v_cmp_le_i32_e32 vcc, v6, v15
	v_or_b32_e32 v6, 50, v0
	s_nop 0
	v_cndmask_b32_e32 v57, v204, v57, vcc
	v_cmp_le_i32_e32 vcc, v6, v15
	v_or_b32_e32 v6, 51, v0
	s_nop 0
	v_cndmask_b32_e32 v58, v204, v58, vcc
	v_cmp_le_i32_e32 vcc, v6, v15
	v_or_b32_e32 v6, 56, v0
	s_nop 0
	v_cndmask_b32_e32 v59, v204, v59, vcc
	v_cmp_le_i32_e32 vcc, v6, v15
	v_or_b32_e32 v6, 57, v0
	s_nop 0
	v_cndmask_b32_e32 v60, v204, v60, vcc
	v_cmp_le_i32_e32 vcc, v6, v15
	v_or_b32_e32 v6, 58, v0
	v_or_b32_e32 v0, 59, v0
	v_cndmask_b32_e32 v61, v204, v61, vcc
	v_cmp_le_i32_e32 vcc, v6, v15
	s_nop 1
	v_cndmask_b32_e32 v62, v204, v62, vcc
	v_cmp_le_i32_e32 vcc, v0, v15
	s_nop 1
	v_cndmask_b32_e32 v63, v204, v63, vcc
